# first K-loop iteration peeled with zero SrcC (no accumulator zeroing); epilogue output stores stay in flight into the next tile
# baseline (speedup 1.0000x reference)
; __device__ __forceinline__ int opaque_tid() { int t = threadIdx.x; asm volatile("" : "+v"(t)); return t; }
; #define PG8_STAGE(bufoff, gbase, voff) do { _Pragma("unroll") for (int _i = 0; _i < 2; ++_i) \
;         __builtin_amdgcn_global_load_lds((const unsigned*)((const char*)(gbase) + (voff)[_i]), (LAS unsigned*)(lds + (bufoff) + ldsw + _i * 8192), 16, 0, 0); } while (0)
; #define PG8_WAIT_V(n) asm volatile("s_waitcnt vmcnt(" #n ")" ::: "memory")
; template <bool PERM>
; __device__ __forceinline__ void gemm_phase(LAS unsigned char* lds, const Gemm g, const Sched& S, const EpiDesc& E, const Ctx& C) {
;     const int tid = opaque_tid(), wid = __builtin_amdgcn_readfirstlane(tid >> 6), lane = tid & 63, wr = wid >> 2, wc = wid & 3, fr = lane & 15, fq = lane >> 4;
;     unsigned voffA[2], voffB[2];
; #pragma unroll
;     for (int i = 0; i < 2; ++i) { int R, Cc; stage_rc(tid * 16 + i * 8192, R, Cc); const int Rb = PERM ? (R & ~31) + perm32(R & 31) : R; voffA[i] = (unsigned)(R * g.lda + Cc) * 2u; voffB[i] = (unsigned)(Rb * g.ldb + Cc) * 2u; }
;     const size_t kstep = (size_t)(BK * 2);
;     const size_t hstepA = (size_t)HALF * g.lda * 2, hstepB = (size_t)HALF * g.ldb * 2;
;     const size_t tstepA = 2 * hstepA, tstepB = 2 * hstepB;
;     const unsigned ldsw = (unsigned)wid * 1024u;
;     const int aoff = lds_byte(wr * 64 + fr, fq * 8), boff = lds_byte(wc * 32 + fr, fq * 8);
;     ...
;     Unit cur, nxt; int ui = 0;
;     if (!S.next(0, cur)) return;
;     f32x4 acc[2][2][4][2];
; #pragma unroll
;     for (int a = 0; a < 2; ++a)
; #pragma unroll
;         for (int b = 0; b < 2; ++b)
; #pragma unroll
;             for (int m = 0; m < 4; ++m)
; #pragma unroll
;                 for (int n = 0; n < 2; ++n) acc[a][b][m][n] = (f32x4){0.f, 0.f, 0.f, 0.f};
;     bf16x8 At[4][2], B0[2][2], B1[2][2];
;     const char* cA = (const char*)g.A + (size_t)cur.pm * tstepA + (size_t)cur.kofs * 2; const char* cB = (const char*)g.Bt + (size_t)cur.pn * tstepB + (size_t)cur.kofs * 2;
;     PG8_STAGE(PG8_SB(0, 0), cB, voffB); PG8_STAGE(PG8_SB(0, 1), cB + hstepB, voffB); PG8_STAGE(PG8_SA(0, 0), cA, voffA); PG8_STAGE(PG8_SA(0, 1), cA + hstepA, voffA);
;     if (wr == 1) PG8_BAR;
;     PG8_WAIT_V(2); PG8_BAR;
;     PG8_STAGE(PG8_SB(1, 0), cB + kstep, voffB); PG8_STAGE(PG8_SA(1, 0), cA + kstep, voffA); PG8_STAGE(PG8_SB(1, 1), cB + hstepB + kstep, voffB);
;     PG8_WAIT_V(6); PG8_BAR;
.LBB0_49:
	s_and_b32 s73, s23, 3
	s_lshl_b32 s74, s28, 6
	s_lshl_b32 s23, s28, 13
	s_lshl_b32 s38, s73, 12
	s_and_b64 s[36:37], s[14:15], exec
	s_mov_b64 s[36:37], 0x80
	s_cselect_b32 s28, 0, 3
	s_add_i32 m0, s69, 0x18000
	v_lshl_add_u64 v[10:11], v[10:11], 0, s[36:37]
	s_waitcnt vmcnt(2)
	s_barrier
	global_load_lds_dwordx4 v[10:11], off
	v_lshl_add_u64 v[6:7], v[6:7], 0, s[36:37]
	s_add_i32 m0, s69, 0x1a000
	s_add_i32 s75, s69, 0x8000
	global_load_lds_dwordx4 v[6:7], off
	v_lshl_add_u64 v[6:7], v[8:9], 0, s[36:37]
	s_mov_b32 m0, s75
	s_add_i32 s76, s69, 0xa000
	global_load_lds_dwordx4 v[6:7], off
	v_lshl_add_u64 v[6:7], v[12:13], 0, s[36:37]
	s_mov_b32 m0, s76
	v_lshl_add_u64 v[4:5], v[4:5], 0, s[36:37]
	global_load_lds_dwordx4 v[6:7], off
	s_add_i32 m0, s69, 0x1c000
	v_lshl_add_u64 v[2:3], v[2:3], 0, s[36:37]
	global_load_lds_dwordx4 v[4:5], off
	s_add_i32 m0, s69, 0x1e000
	v_and_b32_e32 v177, 15, v0
	global_load_lds_dwordx4 v[2:3], off
	v_lshrrev_b32_e32 v2, 1, v0
	v_and_b32_e32 v176, 24, v2
	v_lshlrev_b32_e32 v2, 1, v176
	v_lshlrev_b32_e32 v0, 2, v0
	s_cmpk_lt_u32 s22, 0x100
	v_lshl_or_b32 v2, v177, 6, v2
	v_and_b32_e32 v0, 32, v0
	s_cselect_b64 s[96:97], -1, 0
	s_lshl_b32 s82, s27, 3
	v_bitop3_b32 v4, v2, s23, v0 bitop3:0xde
	v_bitop3_b32 v248, v2, s38, v0 bitop3:0xde
	v_cvt_f32_ubyte0_e32 v0, s82
	v_rcp_iflag_f32_e32 v0, v0
	v_readlane_b32 s38, v254, 51
	s_lshr_b32 s79, s6, 3
	v_readlane_b32 s39, v254, 52
	v_mul_f32_e32 v0, 0x4f7ffffe, v0
	v_cvt_u32_f32_e32 v0, v0
	s_waitcnt lgkmcnt(0)
	s_ashr_i32 s78, s66, 31
	s_and_b32 s80, s6, 6
	s_add_i32 s81, s79, 1
	s_lshl_b64 s[22:23], s[38:39], 20
	v_readlane_b32 s36, v252, 6
	s_add_u32 s16, s36, s22
	v_readlane_b32 s22, v252, 7
	s_addc_u32 s17, s22, s23
	s_sub_i32 s22, 0, s82
	v_readfirstlane_b32 s23, v0
	v_add_u32_e32 v0, v16, v14
	s_waitcnt vmcnt(6)
	s_mul_i32 s22, s22, s23
	v_add_lshl_u32 v2, v0, v15, 1
	v_mov_b32_e32 v3, v1
	v_add_u32_e32 v0, v19, v17
	v_lshl_or_b32 v178, s73, 5, v176
	s_mul_hi_u32 s22, s23, s22
	v_lshl_add_u64 v[180:181], s[42:43], 0, v[2:3]
	v_add_lshl_u32 v2, v0, v18, 1
	v_or_b32_e32 v179, s74, v177
	s_mov_b32 s77, 0
	v_or_b32_e32 v249, 0xfffff800, v178
	s_mov_b32 s7, s19
	s_mul_hi_i32 s53, s38, 0x4040
	s_mul_i32 s52, s38, 0x4040
	s_lshl_b64 s[58:59], s[38:39], 9
	s_add_i32 s83, s23, s22
	v_lshl_add_u64 v[182:183], s[42:43], 0, v[2:3]
	v_add_u32_e32 v250, 0, v4
	s_movk_i32 s44, 0x1800
	s_barrier
	s_waitcnt vmcnt(0)
	s_branch .LBB0_52

; #define PG8_STAGE(bufoff, gbase, voff) do { _Pragma("unroll") for (int _i = 0; _i < 2; ++_i) \
;         __builtin_amdgcn_global_load_lds((const unsigned*)((const char*)(gbase) + (voff)[_i]), (LAS unsigned*)(lds + (bufoff) + ldsw + _i * 8192), 16, 0, 0); } while (0)
; #define PG8_LDA(dst, b, h) do { _Pragma("unroll") for (int m = 0; m < 4; ++m) _Pragma("unroll") for (int k = 0; k < 2; ++k) dst[m][k] = *(const LAS bf16x8*)(lds + PG8_SA(b, h) + aoff + m * 2048 + k * 1024); } while (0)
; #define PG8_LDB(dst, b, h) do { _Pragma("unroll") for (int n = 0; n < 2; ++n) _Pragma("unroll") for (int k = 0; k < 2; ++k) dst[n][k] = *(const LAS bf16x8*)(lds + PG8_SB(b, h) + boff + n * 2048 + k * 1024); } while (0)
; #define PG8_WAIT_V(n) asm volatile("s_waitcnt vmcnt(" #n ")" ::: "memory")
; #define PG8_WAIT_L(n) asm volatile("s_waitcnt lgkmcnt(" #n ")" ::: "memory")
; #define PG8_BAR __builtin_amdgcn_s_barrier()
; #define PG8_SCHED __builtin_amdgcn_sched_barrier(0)
; template <bool PERM>
; __device__ __forceinline__ void gemm_phase(LAS unsigned char* lds, const Gemm g, const Sched& S, const EpiDesc& E, const Ctx& C) {
;     ...
;         for (int t = 0; t < nt; t += 2) {
;             const bool last = (t == nt - 2);
;             const char* a1 = cA + (size_t)(t + 1) * kstep;
;             const char* a2 = last ? nA : cA + (size_t)(t + 2) * kstep; const char* b2 = last ? nB : cB + (size_t)(t + 2) * kstep;
;             const char* a3 = a2 + kstep; const char* b3 = b2 + kstep;
;             PG8_LDB(B0, 0, 0); PG8_LDB(B1, 0, 1); PG8_SCHED; PG8_LDA(At, 0, 0); PG8_STAGE(PG8_SA(1, 1), a1 + hstepA, voffA);
;             PG8_WAIT_V(8); PG8_WAIT_L(0); PG8_BAR; PG8_MMA(0, 0, At, B0); PG8_MMA(0, 1, At, B1); PG8_BAR; PG8_SCHED;
;             PG8_LDA(At, 0, 1); PG8_STAGE(PG8_SB(0, 0), b2, voffB); PG8_STAGE(PG8_SB(0, 1), b2 + hstepB, voffB); PG8_STAGE(PG8_SA(0, 0), a2, voffA);
;             PG8_WAIT_V(8); PG8_WAIT_L(0); PG8_BAR; PG8_MMA(1, 0, At, B0); PG8_MMA(1, 1, At, B1); PG8_BAR; PG8_SCHED;
;     ...
;         if (!has_next) break;
; #pragma unroll
;         for (int a = 0; a < 2; ++a)
; #pragma unroll
;             for (int b = 0; b < 2; ++b)
; #pragma unroll
;                 for (int m = 0; m < 4; ++m)
; #pragma unroll
;                     for (int n = 0; n < 2; ++n) acc[a][b][m][n] = (f32x4){0.f, 0.f, 0.f, 0.f};
;         cur = nxt; cA = nA; cB = nB; ++ui;
;         if (wr == 1) PG8_BAR;
.LBB0_61:
	s_add_i32 s22, s29, -2
	s_add_u32 s2, s2, 0x80
	s_addc_u32 s3, s3, 0
	s_add_u32 s23, s20, 0x100
	s_addc_u32 s36, s21, 0
	s_mov_b32 s20, 0
	s_mov_b64 s[46:47], 0x80
	s_cmp_eq_u32 s24, 2
	s_cbranch_scc1 .Lka_w16
	s_waitcnt vmcnt(0)
	s_branch .Lka_wd
.Lka_w16:
	s_waitcnt vmcnt(16)
.Lka_wd:
.Lka_peel:
	s_add_i32 s37, s20, 2
	s_add_u32 s40, s2, 0x80
	s_addc_u32 s21, s3, 0
	s_add_i32 s61, 0, 0x10000
	s_cmp_eq_u32 s22, s20
	s_cselect_b32 s21, s63, s21
	s_cselect_b32 s20, s62, s40
	v_add_u32_e32 v0, s61, v248
	s_cselect_b32 s41, s65, s36
	s_cselect_b32 s40, s64, s23
	s_add_i32 s88, 0, 0x14000
	ds_read_b128 v[130:133], v0
	ds_read_b128 v[134:137], v0 offset:1024
	ds_read_b128 v[138:141], v0 offset:2048
	ds_read_b128 v[142:145], v0 offset:3072
	v_add_u32_e32 v0, s88, v248
	ds_read_b128 v[146:149], v0
	ds_read_b128 v[150:153], v0 offset:1024
	ds_read_b128 v[154:157], v0 offset:2048
	ds_read_b128 v[158:161], v0 offset:3072
	v_lshl_add_u64 v[192:193], s[2:3], 0, v[180:181]
	s_add_i32 m0, s69, 0xc000
	ds_read_b128 v[162:165], v250
	ds_read_b128 v[184:187], v250 offset:1024
	ds_read_b128 v[188:191], v250 offset:2048
	ds_read_b128 v[196:199], v250 offset:3072
	ds_read_b128 v[200:203], v250 offset:4096
	ds_read_b128 v[204:207], v250 offset:5120
	ds_read_b128 v[208:211], v250 offset:6144
	ds_read_b128 v[212:215], v250 offset:7168
	global_load_lds_dwordx4 v[192:193], off
	v_lshl_add_u64 v[192:193], s[2:3], 0, v[182:183]
	s_add_i32 m0, s69, 0xe000
	s_nop 0
	global_load_lds_dwordx4 v[192:193], off
	s_nop 0
	s_waitcnt lgkmcnt(0)
	s_barrier
	s_setprio 1
	s_waitcnt lgkmcnt(0)
	v_mfma_f32_16x16x32_bf16 v[126:129], v[130:133], v[162:165], 0
	v_mfma_f32_16x16x32_bf16 v[122:125], v[138:141], v[162:165], 0
	v_mfma_f32_16x16x32_bf16 v[110:113], v[130:133], v[188:191], 0
	v_mfma_f32_16x16x32_bf16 v[106:109], v[138:141], v[188:191], 0
	v_mfma_f32_16x16x32_bf16 v[94:97], v[130:133], v[200:203], 0
	v_mfma_f32_16x16x32_bf16 v[90:93], v[138:141], v[200:203], 0
	v_mfma_f32_16x16x32_bf16 v[78:81], v[130:133], v[208:211], 0
	v_mfma_f32_16x16x32_bf16 v[74:77], v[138:141], v[208:211], 0
	v_mfma_f32_16x16x32_bf16 v[126:129], v[134:137], v[184:187], v[126:129]
	v_mfma_f32_16x16x32_bf16 v[122:125], v[142:145], v[184:187], v[122:125]
	v_mfma_f32_16x16x32_bf16 v[110:113], v[134:137], v[196:199], v[110:113]
	v_mfma_f32_16x16x32_bf16 v[106:109], v[142:145], v[196:199], v[106:109]
	v_mfma_f32_16x16x32_bf16 v[94:97], v[134:137], v[204:207], v[94:97]
	v_mfma_f32_16x16x32_bf16 v[90:93], v[142:145], v[204:207], v[90:93]
	v_mfma_f32_16x16x32_bf16 v[78:81], v[134:137], v[212:215], v[78:81]
	v_mfma_f32_16x16x32_bf16 v[74:77], v[142:145], v[212:215], v[74:77]
	s_setprio 0
	s_setprio 1
	v_mfma_f32_16x16x32_bf16 v[118:121], v[146:149], v[162:165], 0
	v_mfma_f32_16x16x32_bf16 v[114:117], v[154:157], v[162:165], 0
	v_mfma_f32_16x16x32_bf16 v[102:105], v[146:149], v[188:191], 0
	v_mfma_f32_16x16x32_bf16 v[98:101], v[154:157], v[188:191], 0
	v_mfma_f32_16x16x32_bf16 v[86:89], v[146:149], v[200:203], 0
	v_mfma_f32_16x16x32_bf16 v[82:85], v[154:157], v[200:203], 0
	v_mfma_f32_16x16x32_bf16 v[70:73], v[146:149], v[208:211], 0
	v_mfma_f32_16x16x32_bf16 v[66:69], v[154:157], v[208:211], 0
	v_mfma_f32_16x16x32_bf16 v[118:121], v[150:153], v[184:187], v[118:121]
	v_mfma_f32_16x16x32_bf16 v[114:117], v[158:161], v[184:187], v[114:117]
	v_mfma_f32_16x16x32_bf16 v[102:105], v[150:153], v[196:199], v[102:105]
	v_mfma_f32_16x16x32_bf16 v[98:101], v[158:161], v[196:199], v[98:101]
	v_mfma_f32_16x16x32_bf16 v[86:89], v[150:153], v[204:207], v[86:89]
	v_mfma_f32_16x16x32_bf16 v[82:85], v[158:161], v[204:207], v[82:85]
	v_mfma_f32_16x16x32_bf16 v[70:73], v[150:153], v[212:215], v[70:73]
	v_mfma_f32_16x16x32_bf16 v[66:69], v[158:161], v[212:215], v[66:69]
	s_setprio 0
	s_barrier
	s_add_i32 s61, s61, s68
	v_lshl_add_u64 v[192:193], s[40:41], 0, v[170:171]
	s_mov_b32 m0, s61
	ds_read_b128 v[162:165], v250 offset:16384
	ds_read_b128 v[184:187], v250 offset:17408
	ds_read_b128 v[188:191], v250 offset:18432
	ds_read_b128 v[196:199], v250 offset:19456
	ds_read_b128 v[200:203], v250 offset:20480
	ds_read_b128 v[204:207], v250 offset:21504
	ds_read_b128 v[208:211], v250 offset:22528
	ds_read_b128 v[212:215], v250 offset:23552
	global_load_lds_dwordx4 v[192:193], off
	s_add_i32 m0, s61, 0x2000
	v_lshl_add_u64 v[216:217], s[40:41], 0, v[174:175]
	s_add_u32 s40, s40, s42
	s_addc_u32 s41, s41, 0
	s_add_i32 s61, s88, s68
	global_load_lds_dwordx4 v[216:217], off
	v_lshl_add_u64 v[218:219], s[40:41], 0, v[170:171]
	s_mov_b32 m0, s61
	v_lshl_add_u64 v[220:221], s[40:41], 0, v[174:175]
	global_load_lds_dwordx4 v[218:219], off
	s_add_i32 m0, s61, 0x2000
	v_lshl_add_u64 v[222:223], s[20:21], 0, v[168:169]
	global_load_lds_dwordx4 v[220:221], off
	s_mov_b32 m0, s69
	v_lshl_add_u64 v[224:225], s[20:21], 0, v[172:173]
	global_load_lds_dwordx4 v[222:223], off
	s_mov_b32 m0, s70
	s_nop 0
	global_load_lds_dwordx4 v[224:225], off
	s_nop 0
	s_waitcnt lgkmcnt(0)
	s_barrier
; #define PG8_STAGE(bufoff, gbase, voff) do { _Pragma("unroll") for (int _i = 0; _i < 2; ++_i) \
;         __builtin_amdgcn_global_load_lds((const unsigned*)((const char*)(gbase) + (voff)[_i]), (LAS unsigned*)(lds + (bufoff) + ldsw + _i * 8192), 16, 0, 0); } while (0)
; #define PG8_LDA(dst, b, h) do { _Pragma("unroll") for (int m = 0; m < 4; ++m) _Pragma("unroll") for (int k = 0; k < 2; ++k) dst[m][k] = *(const LAS bf16x8*)(lds + PG8_SA(b, h) + aoff + m * 2048 + k * 1024); } while (0)
; #define PG8_LDB(dst, b, h) do { _Pragma("unroll") for (int n = 0; n < 2; ++n) _Pragma("unroll") for (int k = 0; k < 2; ++k) dst[n][k] = *(const LAS bf16x8*)(lds + PG8_SB(b, h) + boff + n * 2048 + k * 1024); } while (0)
; #define PG8_MMA(ai, bj, At, Bt) do { __builtin_amdgcn_s_setprio(1); _Pragma("unroll") for (int m = 0; m < 4; ++m) _Pragma("unroll") for (int n = 0; n < 2; ++n) _Pragma("unroll") for (int k = 0; k < 2; ++k) \
;         acc[ai][bj][m][n] = __builtin_amdgcn_mfma_f32_16x16x32_bf16(Bt[n][k], At[m][k], acc[ai][bj][m][n], 0, 0, 0); __builtin_amdgcn_s_setprio(0); } while (0)
; #define PG8_WAIT_V(n) asm volatile("s_waitcnt vmcnt(" #n ")" ::: "memory")
; #define PG8_WAIT_L(n) asm volatile("s_waitcnt lgkmcnt(" #n ")" ::: "memory")
; #define PG8_BAR __builtin_amdgcn_s_barrier()
; #define PG8_SCHED __builtin_amdgcn_sched_barrier(0)
; template <bool PERM>
; __device__ __forceinline__ void gemm_phase(LAS unsigned char* lds, const Gemm g, const Sched& S, const EpiDesc& E, const Ctx& C) {
;     ...
;             PG8_WAIT_V(8); PG8_WAIT_L(0); PG8_BAR; PG8_MMA(1, 0, At, B0); PG8_MMA(1, 1, At, B1); PG8_BAR; PG8_SCHED;
;             PG8_LDB(B0, 1, 0); PG8_LDB(B1, 1, 1); PG8_SCHED; PG8_LDA(At, 1, 0); PG8_STAGE(PG8_SA(0, 1), a2 + hstepA, voffA);
;             PG8_WAIT_V(8); PG8_WAIT_L(0); PG8_BAR; PG8_MMA(0, 0, At, B0); PG8_MMA(0, 1, At, B1); PG8_BAR; PG8_SCHED;
	s_setprio 1
	s_waitcnt lgkmcnt(0)
	v_mfma_f32_16x16x32_bf16 v[62:65], v[130:133], v[162:165], 0
	v_mfma_f32_16x16x32_bf16 v[58:61], v[138:141], v[162:165], 0
	v_mfma_f32_16x16x32_bf16 v[46:49], v[130:133], v[188:191], 0
	v_mfma_f32_16x16x32_bf16 v[42:45], v[138:141], v[188:191], 0
	v_mfma_f32_16x16x32_bf16 v[30:33], v[130:133], v[200:203], 0
	v_mfma_f32_16x16x32_bf16 v[26:29], v[138:141], v[200:203], 0
	v_mfma_f32_16x16x32_bf16 v[14:17], v[130:133], v[208:211], 0
	v_mfma_f32_16x16x32_bf16 v[10:13], v[138:141], v[208:211], 0
	v_mfma_f32_16x16x32_bf16 v[62:65], v[134:137], v[184:187], v[62:65]
	v_mfma_f32_16x16x32_bf16 v[58:61], v[142:145], v[184:187], v[58:61]
	v_mfma_f32_16x16x32_bf16 v[46:49], v[134:137], v[196:199], v[46:49]
	v_mfma_f32_16x16x32_bf16 v[42:45], v[142:145], v[196:199], v[42:45]
	v_mfma_f32_16x16x32_bf16 v[30:33], v[134:137], v[204:207], v[30:33]
	v_mfma_f32_16x16x32_bf16 v[26:29], v[142:145], v[204:207], v[26:29]
	v_mfma_f32_16x16x32_bf16 v[14:17], v[134:137], v[212:215], v[14:17]
	v_mfma_f32_16x16x32_bf16 v[10:13], v[142:145], v[212:215], v[10:13]
	s_setprio 0
	s_setprio 1
	v_mfma_f32_16x16x32_bf16 v[54:57], v[146:149], v[162:165], 0
	v_mfma_f32_16x16x32_bf16 v[50:53], v[154:157], v[162:165], 0
	v_mfma_f32_16x16x32_bf16 v[38:41], v[146:149], v[188:191], 0
	v_mfma_f32_16x16x32_bf16 v[34:37], v[154:157], v[188:191], 0
	v_mfma_f32_16x16x32_bf16 v[22:25], v[146:149], v[200:203], 0
	v_mfma_f32_16x16x32_bf16 v[18:21], v[154:157], v[200:203], 0
	v_mfma_f32_16x16x32_bf16 v[6:9], v[146:149], v[208:211], 0
	v_mfma_f32_16x16x32_bf16 v[2:5], v[154:157], v[208:211], 0
	v_mfma_f32_16x16x32_bf16 v[54:57], v[150:153], v[184:187], v[54:57]
	v_mfma_f32_16x16x32_bf16 v[50:53], v[158:161], v[184:187], v[50:53]
	v_mfma_f32_16x16x32_bf16 v[38:41], v[150:153], v[196:199], v[38:41]
	v_mfma_f32_16x16x32_bf16 v[34:37], v[158:161], v[196:199], v[34:37]
	v_mfma_f32_16x16x32_bf16 v[22:25], v[150:153], v[204:207], v[22:25]
	v_mfma_f32_16x16x32_bf16 v[18:21], v[158:161], v[204:207], v[18:21]
	v_mfma_f32_16x16x32_bf16 v[6:9], v[150:153], v[212:215], v[6:9]
	v_mfma_f32_16x16x32_bf16 v[2:5], v[158:161], v[212:215], v[2:5]
	s_setprio 0
	s_barrier
	s_add_i32 s40, 0, 0x18000
	v_add_u32_e32 v0, s40, v248
	s_add_i32 s41, 0, 0x1c000
	ds_read_b128 v[130:133], v0
	ds_read_b128 v[134:137], v0 offset:1024
	ds_read_b128 v[138:141], v0 offset:2048
	ds_read_b128 v[142:145], v0 offset:3072
	v_add_u32_e32 v0, s41, v248
	ds_read_b128 v[146:149], v0
	ds_read_b128 v[150:153], v0 offset:1024
	ds_read_b128 v[154:157], v0 offset:2048
	ds_read_b128 v[158:161], v0 offset:3072
	s_add_u32 s20, s20, s42
	s_addc_u32 s21, s21, 0
	s_mov_b32 m0, s71
	v_lshl_add_u64 v[226:227], s[20:21], 0, v[168:169]
	ds_read_b128 v[162:165], v250 offset:32768
	ds_read_b128 v[184:187], v250 offset:33792
	ds_read_b128 v[188:191], v250 offset:34816
	ds_read_b128 v[196:199], v250 offset:35840
	ds_read_b128 v[200:203], v250 offset:36864
	ds_read_b128 v[204:207], v250 offset:37888
	ds_read_b128 v[208:211], v250 offset:38912
	ds_read_b128 v[212:215], v250 offset:39936
	global_load_lds_dwordx4 v[226:227], off
	v_lshl_add_u64 v[226:227], s[20:21], 0, v[172:173]
	s_mov_b32 m0, s72
	s_nop 0
	global_load_lds_dwordx4 v[226:227], off
	s_waitcnt vmcnt(8)
	s_waitcnt lgkmcnt(0)
	s_barrier
	s_setprio 1
	s_waitcnt lgkmcnt(0)
	v_mfma_f32_16x16x32_bf16 v[126:129], v[130:133], v[162:165], v[126:129]
	v_mfma_f32_16x16x32_bf16 v[122:125], v[138:141], v[162:165], v[122:125]
	v_mfma_f32_16x16x32_bf16 v[110:113], v[130:133], v[188:191], v[110:113]
	v_mfma_f32_16x16x32_bf16 v[106:109], v[138:141], v[188:191], v[106:109]
	v_mfma_f32_16x16x32_bf16 v[94:97], v[130:133], v[200:203], v[94:97]
	v_mfma_f32_16x16x32_bf16 v[90:93], v[138:141], v[200:203], v[90:93]
	v_mfma_f32_16x16x32_bf16 v[78:81], v[130:133], v[208:211], v[78:81]
	v_mfma_f32_16x16x32_bf16 v[74:77], v[138:141], v[208:211], v[74:77]
	v_mfma_f32_16x16x32_bf16 v[126:129], v[134:137], v[184:187], v[126:129]
	v_mfma_f32_16x16x32_bf16 v[122:125], v[142:145], v[184:187], v[122:125]
	v_mfma_f32_16x16x32_bf16 v[110:113], v[134:137], v[196:199], v[110:113]
	v_mfma_f32_16x16x32_bf16 v[106:109], v[142:145], v[196:199], v[106:109]
	v_mfma_f32_16x16x32_bf16 v[94:97], v[134:137], v[204:207], v[94:97]
	v_mfma_f32_16x16x32_bf16 v[90:93], v[142:145], v[204:207], v[90:93]
	v_mfma_f32_16x16x32_bf16 v[78:81], v[134:137], v[212:215], v[78:81]
	v_mfma_f32_16x16x32_bf16 v[74:77], v[142:145], v[212:215], v[74:77]
	s_setprio 0
	s_setprio 1
	v_mfma_f32_16x16x32_bf16 v[118:121], v[146:149], v[162:165], v[118:121]
	v_mfma_f32_16x16x32_bf16 v[114:117], v[154:157], v[162:165], v[114:117]
	v_mfma_f32_16x16x32_bf16 v[102:105], v[146:149], v[188:191], v[102:105]
	v_mfma_f32_16x16x32_bf16 v[98:101], v[154:157], v[188:191], v[98:101]
	v_mfma_f32_16x16x32_bf16 v[86:89], v[146:149], v[200:203], v[86:89]
	v_mfma_f32_16x16x32_bf16 v[82:85], v[154:157], v[200:203], v[82:85]
	v_mfma_f32_16x16x32_bf16 v[70:73], v[146:149], v[208:211], v[70:73]
	v_mfma_f32_16x16x32_bf16 v[66:69], v[154:157], v[208:211], v[66:69]
	v_mfma_f32_16x16x32_bf16 v[118:121], v[150:153], v[184:187], v[118:121]
	v_mfma_f32_16x16x32_bf16 v[114:117], v[158:161], v[184:187], v[114:117]
	v_mfma_f32_16x16x32_bf16 v[102:105], v[150:153], v[196:199], v[102:105]
	v_mfma_f32_16x16x32_bf16 v[98:101], v[158:161], v[196:199], v[98:101]
	v_mfma_f32_16x16x32_bf16 v[86:89], v[150:153], v[204:207], v[86:89]
	v_mfma_f32_16x16x32_bf16 v[82:85], v[158:161], v[204:207], v[82:85]
	v_mfma_f32_16x16x32_bf16 v[70:73], v[150:153], v[212:215], v[70:73]
	v_mfma_f32_16x16x32_bf16 v[66:69], v[158:161], v[212:215], v[66:69]
	s_setprio 0
	s_barrier
; #define PG8_STAGE(bufoff, gbase, voff) do { _Pragma("unroll") for (int _i = 0; _i < 2; ++_i) \
;         __builtin_amdgcn_global_load_lds((const unsigned*)((const char*)(gbase) + (voff)[_i]), (LAS unsigned*)(lds + (bufoff) + ldsw + _i * 8192), 16, 0, 0); } while (0)
; #define PG8_LDA(dst, b, h) do { _Pragma("unroll") for (int m = 0; m < 4; ++m) _Pragma("unroll") for (int k = 0; k < 2; ++k) dst[m][k] = *(const LAS bf16x8*)(lds + PG8_SA(b, h) + aoff + m * 2048 + k * 1024); } while (0)
; #define PG8_MMA(ai, bj, At, Bt) do { __builtin_amdgcn_s_setprio(1); _Pragma("unroll") for (int m = 0; m < 4; ++m) _Pragma("unroll") for (int n = 0; n < 2; ++n) _Pragma("unroll") for (int k = 0; k < 2; ++k) \
;         acc[ai][bj][m][n] = __builtin_amdgcn_mfma_f32_16x16x32_bf16(Bt[n][k], At[m][k], acc[ai][bj][m][n], 0, 0, 0); __builtin_amdgcn_s_setprio(0); } while (0)
; #define PG8_WAIT_V(n) asm volatile("s_waitcnt vmcnt(" #n ")" ::: "memory")
; #define PG8_WAIT_L(n) asm volatile("s_waitcnt lgkmcnt(" #n ")" ::: "memory")
; #define PG8_BAR __builtin_amdgcn_s_barrier()
; #define PG8_SCHED __builtin_amdgcn_sched_barrier(0)
; template <bool PERM>
; __device__ __forceinline__ void gemm_phase(LAS unsigned char* lds, const Gemm g, const Sched& S, const EpiDesc& E, const Ctx& C) {
;     ...
;             PG8_LDA(At, 1, 1); PG8_STAGE(PG8_SB(1, 0), b3, voffB); PG8_STAGE(PG8_SB(1, 1), b3 + hstepB, voffB); PG8_STAGE(PG8_SA(1, 0), a3, voffA);
;             PG8_WAIT_V(8); PG8_WAIT_L(0); PG8_BAR; PG8_MMA(1, 0, At, B0); PG8_MMA(1, 1, At, B1); PG8_BAR; PG8_SCHED;
;         }
	s_add_i32 s20, s40, s68
	v_lshl_add_u64 v[192:193], v[192:193], 0, s[46:47]
	s_mov_b32 m0, s20
	ds_read_b128 v[162:165], v250 offset:49152
	ds_read_b128 v[184:187], v250 offset:50176
	ds_read_b128 v[188:191], v250 offset:51200
	ds_read_b128 v[196:199], v250 offset:52224
	ds_read_b128 v[200:203], v250 offset:53248
	ds_read_b128 v[204:207], v250 offset:54272
	ds_read_b128 v[208:211], v250 offset:55296
	ds_read_b128 v[212:215], v250 offset:56320
	global_load_lds_dwordx4 v[192:193], off
	v_lshl_add_u64 v[192:193], v[216:217], 0, s[46:47]
	s_add_i32 m0, s20, 0x2000
	s_add_i32 s20, s41, s68
	global_load_lds_dwordx4 v[192:193], off
	v_lshl_add_u64 v[192:193], v[218:219], 0, s[46:47]
	s_mov_b32 m0, s20
	s_nop 0
	global_load_lds_dwordx4 v[192:193], off
	v_lshl_add_u64 v[192:193], v[220:221], 0, s[46:47]
	s_add_i32 m0, s20, 0x2000
	s_nop 0
	global_load_lds_dwordx4 v[192:193], off
	v_lshl_add_u64 v[192:193], v[222:223], 0, s[46:47]
	s_mov_b32 m0, s75
	s_nop 0
	global_load_lds_dwordx4 v[192:193], off
	v_lshl_add_u64 v[192:193], v[224:225], 0, s[46:47]
	s_mov_b32 m0, s76
	s_nop 0
	global_load_lds_dwordx4 v[192:193], off
	s_waitcnt vmcnt(8)
	s_waitcnt lgkmcnt(0)
	s_barrier
	s_setprio 1
	s_waitcnt lgkmcnt(0)
	v_mfma_f32_16x16x32_bf16 v[62:65], v[130:133], v[162:165], v[62:65]
	v_mfma_f32_16x16x32_bf16 v[58:61], v[138:141], v[162:165], v[58:61]
	v_mfma_f32_16x16x32_bf16 v[46:49], v[130:133], v[188:191], v[46:49]
	v_mfma_f32_16x16x32_bf16 v[42:45], v[138:141], v[188:191], v[42:45]
	v_mfma_f32_16x16x32_bf16 v[30:33], v[130:133], v[200:203], v[30:33]
	v_mfma_f32_16x16x32_bf16 v[26:29], v[138:141], v[200:203], v[26:29]
	v_mfma_f32_16x16x32_bf16 v[14:17], v[130:133], v[208:211], v[14:17]
	v_mfma_f32_16x16x32_bf16 v[10:13], v[138:141], v[208:211], v[10:13]
	v_mfma_f32_16x16x32_bf16 v[62:65], v[134:137], v[184:187], v[62:65]
	v_mfma_f32_16x16x32_bf16 v[58:61], v[142:145], v[184:187], v[58:61]
	v_mfma_f32_16x16x32_bf16 v[46:49], v[134:137], v[196:199], v[46:49]
	v_mfma_f32_16x16x32_bf16 v[42:45], v[142:145], v[196:199], v[42:45]
	v_mfma_f32_16x16x32_bf16 v[30:33], v[134:137], v[204:207], v[30:33]
	v_mfma_f32_16x16x32_bf16 v[26:29], v[142:145], v[204:207], v[26:29]
	v_mfma_f32_16x16x32_bf16 v[14:17], v[134:137], v[212:215], v[14:17]
	v_mfma_f32_16x16x32_bf16 v[10:13], v[142:145], v[212:215], v[10:13]
	s_setprio 0
	s_setprio 1
	v_mfma_f32_16x16x32_bf16 v[54:57], v[146:149], v[162:165], v[54:57]
	v_mfma_f32_16x16x32_bf16 v[50:53], v[154:157], v[162:165], v[50:53]
	v_mfma_f32_16x16x32_bf16 v[38:41], v[146:149], v[188:191], v[38:41]
	v_mfma_f32_16x16x32_bf16 v[34:37], v[154:157], v[188:191], v[34:37]
	v_mfma_f32_16x16x32_bf16 v[22:25], v[146:149], v[200:203], v[22:25]
	v_mfma_f32_16x16x32_bf16 v[18:21], v[154:157], v[200:203], v[18:21]
	v_mfma_f32_16x16x32_bf16 v[6:9], v[146:149], v[208:211], v[6:9]
	v_mfma_f32_16x16x32_bf16 v[2:5], v[154:157], v[208:211], v[2:5]
	v_mfma_f32_16x16x32_bf16 v[54:57], v[150:153], v[184:187], v[54:57]
	v_mfma_f32_16x16x32_bf16 v[50:53], v[158:161], v[184:187], v[50:53]
	v_mfma_f32_16x16x32_bf16 v[38:41], v[150:153], v[196:199], v[38:41]
	v_mfma_f32_16x16x32_bf16 v[34:37], v[158:161], v[196:199], v[34:37]
	v_mfma_f32_16x16x32_bf16 v[22:25], v[150:153], v[204:207], v[22:25]
	v_mfma_f32_16x16x32_bf16 v[18:21], v[158:161], v[204:207], v[18:21]
	v_mfma_f32_16x16x32_bf16 v[6:9], v[150:153], v[212:215], v[6:9]
	v_mfma_f32_16x16x32_bf16 v[2:5], v[158:161], v[212:215], v[2:5]
	s_setprio 0
	s_barrier
	s_add_u32 s2, s2, 0x100
	s_addc_u32 s3, s3, 0
	s_add_u32 s23, s23, 0x100
	s_addc_u32 s36, s36, 0
	s_cmp_ge_i32 s37, s29
	s_mov_b32 s20, s37
	s_cbranch_scc1 .Lka_exit

; #define PG8_BAR __builtin_amdgcn_s_barrier()
; template <bool PERM>
; __device__ __forceinline__ void gemm_phase(LAS unsigned char* lds, const Gemm g, const Sched& S, const EpiDesc& E, const Ctx& C) {
;     ...
;         if (wr == 0) PG8_BAR;
;         if (PERM) {
;             if ((PERM_MASK & 1) && E.kind == EK_SWIGLU) epilogue_p<EK_SWIGLU>(acc, cur, E, C, wr, wc, fr, fq);
;             else if ((PERM_MASK & 2) && E.kind == EK_RESID) epilogue_p<EK_RESID>(acc, cur, E, C, wr, wc, fr, fq);
;             else if ((PERM_MASK & 4) && E.kind == EK_PROJ) epilogue_p<EK_PROJ>(acc, cur, E, C, wr, wc, fr, fq);
;             else if ((PERM_MASK & 8) && E.kind == EK_BRANCH) epilogue_p<EK_BRANCH>(acc, cur, E, C, wr, wc, fr, fq);
.Lka_exit:
	v_readlane_b32 s88, v254, 35
	v_readlane_b32 s89, v254, 36
	s_and_b64 vcc, exec, s[96:97]
	s_cbranch_vccz .LBB0_65

; __device__ __forceinline__ int opaque_tid() { int t = threadIdx.x; asm volatile("" : "+v"(t)); return t; }
; #define PG8_STAGE(bufoff, gbase, voff) do { _Pragma("unroll") for (int _i = 0; _i < 2; ++_i) \
;         __builtin_amdgcn_global_load_lds((const unsigned*)((const char*)(gbase) + (voff)[_i]), (LAS unsigned*)(lds + (bufoff) + ldsw + _i * 8192), 16, 0, 0); } while (0)
; #define PG8_WAIT_V(n) asm volatile("s_waitcnt vmcnt(" #n ")" ::: "memory")
; template <bool PERM>
; __device__ __forceinline__ void gemm_phase(LAS unsigned char* lds, const Gemm g, const Sched& S, const EpiDesc& E, const Ctx& C) {
;     const int tid = opaque_tid(), wid = __builtin_amdgcn_readfirstlane(tid >> 6), lane = tid & 63, wr = wid >> 2, wc = wid & 3, fr = lane & 15, fq = lane >> 4;
;     unsigned voffA[2], voffB[2];
; #pragma unroll
;     for (int i = 0; i < 2; ++i) { int R, Cc; stage_rc(tid * 16 + i * 8192, R, Cc); const int Rb = PERM ? (R & ~31) + perm32(R & 31) : R; voffA[i] = (unsigned)(R * g.lda + Cc) * 2u; voffB[i] = (unsigned)(Rb * g.ldb + Cc) * 2u; }
;     const size_t kstep = (size_t)(BK * 2);
;     const size_t hstepA = (size_t)HALF * g.lda * 2, hstepB = (size_t)HALF * g.ldb * 2;
;     const size_t tstepA = 2 * hstepA, tstepB = 2 * hstepB;
;     const unsigned ldsw = (unsigned)wid * 1024u;
;     const int aoff = lds_byte(wr * 64 + fr, fq * 8), boff = lds_byte(wc * 32 + fr, fq * 8);
;     ...
;     Unit cur, nxt; int ui = 0;
;     if (!S.next(0, cur)) return;
;     f32x4 acc[2][2][4][2];
; #pragma unroll
;     for (int a = 0; a < 2; ++a)
; #pragma unroll
;         for (int b = 0; b < 2; ++b)
; #pragma unroll
;             for (int m = 0; m < 4; ++m)
; #pragma unroll
;                 for (int n = 0; n < 2; ++n) acc[a][b][m][n] = (f32x4){0.f, 0.f, 0.f, 0.f};
;     bf16x8 At[4][2], B0[2][2], B1[2][2];
;     const char* cA = (const char*)g.A + (size_t)cur.pm * tstepA + (size_t)cur.kofs * 2; const char* cB = (const char*)g.Bt + (size_t)cur.pn * tstepB + (size_t)cur.kofs * 2;
;     PG8_STAGE(PG8_SB(0, 0), cB, voffB); PG8_STAGE(PG8_SB(0, 1), cB + hstepB, voffB); PG8_STAGE(PG8_SA(0, 0), cA, voffA); PG8_STAGE(PG8_SA(0, 1), cA + hstepA, voffA);
;     if (wr == 1) PG8_BAR;
;     PG8_WAIT_V(2); PG8_BAR;
;     PG8_STAGE(PG8_SB(1, 0), cB + kstep, voffB); PG8_STAGE(PG8_SA(1, 0), cA + kstep, voffA); PG8_STAGE(PG8_SB(1, 1), cB + hstepB + kstep, voffB);
;     PG8_WAIT_V(6); PG8_BAR;
.LBB0_228:
	s_mov_b64 s[48:49], 0x80
	s_add_i32 m0, s70, 0x18000
	v_lshl_add_u64 v[2:3], v[2:3], 0, s[48:49]
	s_waitcnt vmcnt(2)
	s_barrier
	global_load_lds_dwordx4 v[2:3], off
	v_lshl_add_u64 v[2:3], v[4:5], 0, s[48:49]
	s_add_i32 m0, s70, 0x1a000
	s_add_i32 s75, s70, 0x8000
	global_load_lds_dwordx4 v[2:3], off
	v_lshl_add_u64 v[2:3], v[10:11], 0, s[48:49]
	s_mov_b32 m0, s75
	s_add_i32 s76, s70, 0xa000
	global_load_lds_dwordx4 v[2:3], off
	v_lshl_add_u64 v[2:3], v[12:13], 0, s[48:49]
	s_mov_b32 m0, s76
	v_bfe_u32 v20, v19, 4, 2
	global_load_lds_dwordx4 v[2:3], off
	s_add_i32 m0, s70, 0x1c000
	v_lshl_add_u64 v[2:3], v[6:7], 0, s[48:49]
	global_load_lds_dwordx4 v[2:3], off
	v_lshl_add_u64 v[2:3], v[8:9], 0, s[48:49]
	s_add_i32 m0, s70, 0x1e000
	v_and_b32_e32 v172, 15, v19
	global_load_lds_dwordx4 v[2:3], off
	v_lshlrev_b32_e32 v21, 4, v20
	v_lshlrev_b32_e32 v19, 2, v19
	s_and_b32 s22, s22, 3
	s_lshl_b32 s74, s23, 6
	v_lshl_or_b32 v21, v172, 6, v21
	s_lshl_b32 s23, s23, 13
	v_and_b32_e32 v19, 32, v19
	v_bitop3_b32 v22, v21, s23, v19 bitop3:0xde
	s_lshl_b32 s23, s22, 12
	v_lshlrev_b32_e32 v4, 2, v20
	s_cmpk_lt_u32 s11, 0x100
	v_lshl_or_b32 v175, s22, 5, v4
	s_cselect_b64 s[56:57], -1, 0
	v_lshlrev_b32_e32 v2, 1, v175
	v_mov_b32_e32 v3, v1
	s_lshl_b32 s27, s27, 3
	v_lshl_add_u64 v[138:139], s[90:91], 0, v[2:3]
	v_cvt_f32_ubyte0_e32 v2, s27
	v_rcp_iflag_f32_e32 v2, v2
	v_bitop3_b32 v174, v21, s23, v19 bitop3:0xde
	v_lshl_or_b32 v176, s22, 4, v4
	s_sub_i32 s22, 0, s27
	v_mul_f32_e32 v2, 0x4f7ffffe, v2
	v_cvt_u32_f32_e32 v2, v2
	v_add_u32_e32 v0, v15, v0
	s_waitcnt vmcnt(6)
	s_lshr_b32 s79, s6, 3
	v_readfirstlane_b32 s23, v2
	s_mul_i32 s22, s22, s23
	v_add_lshl_u32 v2, v0, v14, 1
	v_add_u32_e32 v0, v18, v16
	s_mul_hi_u32 s22, s23, s22
	v_lshl_add_u64 v[140:141], s[18:19], 0, v[2:3]
	v_add_lshl_u32 v2, v0, v17, 1
	v_readlane_b32 s16, v251, 9
	v_or_b32_e32 v173, s74, v172
	s_mov_b32 s77, 0
	v_cmp_eq_u32_e64 s[38:39], 0, v20
	s_waitcnt lgkmcnt(0)
	s_ashr_i32 s78, s66, 31
	s_mov_b32 s7, s19
	s_and_b32 s80, s6, 6
	s_add_i32 s81, s79, 1
	s_mov_b32 s11, s10
	s_mov_b32 s58, s10
	s_mov_b32 s59, s10
	s_add_i32 s82, s23, s22
	v_lshl_add_u64 v[142:143], s[18:19], 0, v[2:3]
	v_add_u32_e32 v177, 0, v22
	s_movk_i32 s46, 0x1600
	v_readlane_b32 s17, v251, 10
	s_barrier
	s_waitcnt vmcnt(0)
	s_branch .LBB0_231

; #define PG8_BAR __builtin_amdgcn_s_barrier()
; template <bool PERM>
; __device__ __forceinline__ void gemm_phase(LAS unsigned char* lds, const Gemm g, const Sched& S, const EpiDesc& E, const Ctx& C) {
;     ...
;         if (!has_next) break;
; #pragma unroll
;         for (int a = 0; a < 2; ++a)
; #pragma unroll
;             for (int b = 0; b < 2; ++b)
; #pragma unroll
;                 for (int m = 0; m < 4; ++m)
; #pragma unroll
;                     for (int n = 0; n < 2; ++n) acc[a][b][m][n] = (f32x4){0.f, 0.f, 0.f, 0.f};
;         cur = nxt; cA = nA; cB = nB; ++ui;
;         if (wr == 1) PG8_BAR;
.LBB0_240:
	s_add_i32 s22, s28, -2
	s_add_u32 s2, s2, 0x80
	s_addc_u32 s3, s3, 0
	s_add_u32 s23, s20, 0x100
	s_addc_u32 s29, s21, 0
	s_mov_b32 s20, 0
	s_cmp_lt_i32 s24, 1
	s_cbranch_scc1 .Lkb_w16
	s_waitcnt vmcnt(0)
	s_branch .Lkb_wd

; #define PG8_STAGE(bufoff, gbase, voff) do { _Pragma("unroll") for (int _i = 0; _i < 2; ++_i) \
;         __builtin_amdgcn_global_load_lds((const unsigned*)((const char*)(gbase) + (voff)[_i]), (LAS unsigned*)(lds + (bufoff) + ldsw + _i * 8192), 16, 0, 0); } while (0)
; #define PG8_LDA(dst, b, h) do { _Pragma("unroll") for (int m = 0; m < 4; ++m) _Pragma("unroll") for (int k = 0; k < 2; ++k) dst[m][k] = *(const LAS bf16x8*)(lds + PG8_SA(b, h) + aoff + m * 2048 + k * 1024); } while (0)
; #define PG8_LDB(dst, b, h) do { _Pragma("unroll") for (int n = 0; n < 2; ++n) _Pragma("unroll") for (int k = 0; k < 2; ++k) dst[n][k] = *(const LAS bf16x8*)(lds + PG8_SB(b, h) + boff + n * 2048 + k * 1024); } while (0)
; #define PG8_MMA(ai, bj, At, Bt) do { __builtin_amdgcn_s_setprio(1); _Pragma("unroll") for (int m = 0; m < 4; ++m) _Pragma("unroll") for (int n = 0; n < 2; ++n) _Pragma("unroll") for (int k = 0; k < 2; ++k) \
;         acc[ai][bj][m][n] = __builtin_amdgcn_mfma_f32_16x16x32_bf16(Bt[n][k], At[m][k], acc[ai][bj][m][n], 0, 0, 0); __builtin_amdgcn_s_setprio(0); } while (0)
; #define PG8_WAIT_V(n) asm volatile("s_waitcnt vmcnt(" #n ")" ::: "memory")
; template <bool PERM>
; __device__ __forceinline__ void gemm_phase(LAS unsigned char* lds, const Gemm g, const Sched& S, const EpiDesc& E, const Ctx& C) {
;     ...
;         const bool has_next = S.next(ui + 1, nxt);
;         const char* nA = has_next ? (const char*)g.A + (size_t)nxt.pm * tstepA + (size_t)nxt.kofs * 2 : cA; const char* nB = has_next ? (const char*)g.Bt + (size_t)nxt.pn * tstepB + (size_t)nxt.kofs * 2 : cB;
;         const int nt = cur.nt;
;         for (int t = 0; t < nt; t += 2) {
;             const bool last = (t == nt - 2);
;             const char* a1 = cA + (size_t)(t + 1) * kstep;
;             const char* a2 = last ? nA : cA + (size_t)(t + 2) * kstep; const char* b2 = last ? nB : cB + (size_t)(t + 2) * kstep;
;             const char* a3 = a2 + kstep; const char* b3 = b2 + kstep;
;             PG8_LDB(B0, 0, 0); PG8_LDB(B1, 0, 1); PG8_SCHED; PG8_LDA(At, 0, 0); PG8_STAGE(PG8_SA(1, 1), a1 + hstepA, voffA);
;             PG8_WAIT_V(8); PG8_WAIT_L(0); PG8_BAR; PG8_MMA(0, 0, At, B0); PG8_MMA(0, 1, At, B1); PG8_BAR; PG8_SCHED;
;             PG8_LDA(At, 0, 1); PG8_STAGE(PG8_SB(0, 0), b2, voffB); PG8_STAGE(PG8_SB(0, 1), b2 + hstepB, voffB); PG8_STAGE(PG8_SA(0, 0), a2, voffA);
.Lkb_wd:
.Lkb_peel:
	s_add_i32 s36, s20, 2
	s_add_u32 s37, s2, 0x80
	s_addc_u32 s21, s3, 0
	s_add_i32 s44, 0, 0x10000
	s_cmp_eq_u32 s22, s20
	s_cselect_b32 s21, s63, s21
	s_cselect_b32 s20, s62, s37
	v_add_u32_e32 v0, s44, v174
	s_cselect_b32 s43, s65, s29
	s_cselect_b32 s42, s64, s23
	s_add_i32 s37, 0, 0x14000
	s_waitcnt lgkmcnt(0)
	ds_read_b128 v[130:133], v0
	ds_read_b128 v[144:147], v0 offset:1024
	ds_read_b128 v[148:151], v0 offset:2048
	ds_read_b128 v[152:155], v0 offset:3072
	v_add_u32_e32 v0, s37, v174
	ds_read_b128 v[156:159], v0
	ds_read_b128 v[160:163], v0 offset:1024
	ds_read_b128 v[168:171], v0 offset:2048
	ds_read_b128 v[178:181], v0 offset:3072
	v_lshl_add_u64 v[164:165], s[2:3], 0, v[140:141]
	s_add_i32 m0, s70, 0xc000
	ds_read_b128 v[182:185], v177
	ds_read_b128 v[186:189], v177 offset:1024
	ds_read_b128 v[190:193], v177 offset:2048
	ds_read_b128 v[196:199], v177 offset:3072
	ds_read_b128 v[200:203], v177 offset:4096
	ds_read_b128 v[204:207], v177 offset:5120
	ds_read_b128 v[208:211], v177 offset:6144
	ds_read_b128 v[212:215], v177 offset:7168
	global_load_lds_dwordx4 v[164:165], off
	v_lshl_add_u64 v[164:165], s[2:3], 0, v[142:143]
	s_add_i32 m0, s70, 0xe000
	s_nop 0
	global_load_lds_dwordx4 v[164:165], off
	s_nop 0
	s_waitcnt lgkmcnt(0)
	s_barrier
	s_setprio 1
	s_waitcnt lgkmcnt(0)
	v_mfma_f32_16x16x32_bf16 v[122:125], v[130:133], v[182:185], 0
	v_mfma_f32_16x16x32_bf16 v[126:129], v[148:151], v[182:185], 0
	v_mfma_f32_16x16x32_bf16 v[106:109], v[130:133], v[190:193], 0
	v_mfma_f32_16x16x32_bf16 v[110:113], v[148:151], v[190:193], 0
	v_mfma_f32_16x16x32_bf16 v[90:93], v[130:133], v[200:203], 0
	v_mfma_f32_16x16x32_bf16 v[94:97], v[148:151], v[200:203], 0
	v_mfma_f32_16x16x32_bf16 v[74:77], v[130:133], v[208:211], 0
	v_mfma_f32_16x16x32_bf16 v[78:81], v[148:151], v[208:211], 0
	v_mfma_f32_16x16x32_bf16 v[122:125], v[144:147], v[186:189], v[122:125]
	v_mfma_f32_16x16x32_bf16 v[126:129], v[152:155], v[186:189], v[126:129]
	v_mfma_f32_16x16x32_bf16 v[106:109], v[144:147], v[196:199], v[106:109]
	v_mfma_f32_16x16x32_bf16 v[110:113], v[152:155], v[196:199], v[110:113]
	v_mfma_f32_16x16x32_bf16 v[90:93], v[144:147], v[204:207], v[90:93]
	v_mfma_f32_16x16x32_bf16 v[94:97], v[152:155], v[204:207], v[94:97]
	v_mfma_f32_16x16x32_bf16 v[74:77], v[144:147], v[212:215], v[74:77]
	v_mfma_f32_16x16x32_bf16 v[78:81], v[152:155], v[212:215], v[78:81]
	s_setprio 0
	s_setprio 1
	v_mfma_f32_16x16x32_bf16 v[114:117], v[156:159], v[182:185], 0
	v_mfma_f32_16x16x32_bf16 v[118:121], v[168:171], v[182:185], 0
	v_mfma_f32_16x16x32_bf16 v[98:101], v[156:159], v[190:193], 0
	v_mfma_f32_16x16x32_bf16 v[102:105], v[168:171], v[190:193], 0
	v_mfma_f32_16x16x32_bf16 v[82:85], v[156:159], v[200:203], 0
	v_mfma_f32_16x16x32_bf16 v[86:89], v[168:171], v[200:203], 0
	v_mfma_f32_16x16x32_bf16 v[66:69], v[156:159], v[208:211], 0
	v_mfma_f32_16x16x32_bf16 v[70:73], v[168:171], v[208:211], 0
	v_mfma_f32_16x16x32_bf16 v[114:117], v[160:163], v[186:189], v[114:117]
	v_mfma_f32_16x16x32_bf16 v[118:121], v[178:181], v[186:189], v[118:121]
	v_mfma_f32_16x16x32_bf16 v[98:101], v[160:163], v[196:199], v[98:101]
	v_mfma_f32_16x16x32_bf16 v[102:105], v[178:181], v[196:199], v[102:105]
	v_mfma_f32_16x16x32_bf16 v[82:85], v[160:163], v[204:207], v[82:85]
	v_mfma_f32_16x16x32_bf16 v[86:89], v[178:181], v[204:207], v[86:89]
	v_mfma_f32_16x16x32_bf16 v[66:69], v[160:163], v[212:215], v[66:69]
	v_mfma_f32_16x16x32_bf16 v[70:73], v[178:181], v[212:215], v[70:73]
	s_setprio 0
	s_barrier
	s_add_i32 s44, s44, s69
	v_lshl_add_u64 v[164:165], s[42:43], 0, v[134:135]
	s_mov_b32 m0, s44
	ds_read_b128 v[182:185], v177 offset:16384
	ds_read_b128 v[186:189], v177 offset:17408
	ds_read_b128 v[190:193], v177 offset:18432
	ds_read_b128 v[196:199], v177 offset:19456
	ds_read_b128 v[200:203], v177 offset:20480
	ds_read_b128 v[204:207], v177 offset:21504
	ds_read_b128 v[208:211], v177 offset:22528
	ds_read_b128 v[212:215], v177 offset:23552
	global_load_lds_dwordx4 v[164:165], off
	s_add_i32 m0, s44, 0x2000
	v_lshl_add_u64 v[216:217], s[42:43], 0, v[136:137]
	s_add_u32 s42, s42, s18
	s_addc_u32 s43, s43, 0
	s_add_i32 s37, s37, s69
	global_load_lds_dwordx4 v[216:217], off
	v_lshl_add_u64 v[218:219], s[42:43], 0, v[134:135]
	s_mov_b32 m0, s37
	v_lshl_add_u64 v[220:221], s[42:43], 0, v[136:137]
	global_load_lds_dwordx4 v[218:219], off
	s_add_i32 m0, s37, 0x2000
	v_lshl_add_u64 v[222:223], s[20:21], 0, v[134:135]
	global_load_lds_dwordx4 v[220:221], off
	s_mov_b32 m0, s70
	v_lshl_add_u64 v[224:225], s[20:21], 0, v[136:137]
	global_load_lds_dwordx4 v[222:223], off
	s_mov_b32 m0, s71
	s_nop 0
	global_load_lds_dwordx4 v[224:225], off
	s_nop 0
	s_waitcnt lgkmcnt(0)
	s_barrier
; #define PG8_STAGE(bufoff, gbase, voff) do { _Pragma("unroll") for (int _i = 0; _i < 2; ++_i) \
;         __builtin_amdgcn_global_load_lds((const unsigned*)((const char*)(gbase) + (voff)[_i]), (LAS unsigned*)(lds + (bufoff) + ldsw + _i * 8192), 16, 0, 0); } while (0)
; #define PG8_LDA(dst, b, h) do { _Pragma("unroll") for (int m = 0; m < 4; ++m) _Pragma("unroll") for (int k = 0; k < 2; ++k) dst[m][k] = *(const LAS bf16x8*)(lds + PG8_SA(b, h) + aoff + m * 2048 + k * 1024); } while (0)
; #define PG8_LDB(dst, b, h) do { _Pragma("unroll") for (int n = 0; n < 2; ++n) _Pragma("unroll") for (int k = 0; k < 2; ++k) dst[n][k] = *(const LAS bf16x8*)(lds + PG8_SB(b, h) + boff + n * 2048 + k * 1024); } while (0)
; #define PG8_MMA(ai, bj, At, Bt) do { __builtin_amdgcn_s_setprio(1); _Pragma("unroll") for (int m = 0; m < 4; ++m) _Pragma("unroll") for (int n = 0; n < 2; ++n) _Pragma("unroll") for (int k = 0; k < 2; ++k) \
;         acc[ai][bj][m][n] = __builtin_amdgcn_mfma_f32_16x16x32_bf16(Bt[n][k], At[m][k], acc[ai][bj][m][n], 0, 0, 0); __builtin_amdgcn_s_setprio(0); } while (0)
; #define PG8_WAIT_V(n) asm volatile("s_waitcnt vmcnt(" #n ")" ::: "memory")
; #define PG8_WAIT_L(n) asm volatile("s_waitcnt lgkmcnt(" #n ")" ::: "memory")
; #define PG8_BAR __builtin_amdgcn_s_barrier()
; #define PG8_SCHED __builtin_amdgcn_sched_barrier(0)
; template <bool PERM>
; __device__ __forceinline__ void gemm_phase(LAS unsigned char* lds, const Gemm g, const Sched& S, const EpiDesc& E, const Ctx& C) {
;     ...
;             PG8_WAIT_V(8); PG8_WAIT_L(0); PG8_BAR; PG8_MMA(1, 0, At, B0); PG8_MMA(1, 1, At, B1); PG8_BAR; PG8_SCHED;
;             PG8_LDB(B0, 1, 0); PG8_LDB(B1, 1, 1); PG8_SCHED; PG8_LDA(At, 1, 0); PG8_STAGE(PG8_SA(0, 1), a2 + hstepA, voffA);
;             PG8_WAIT_V(8); PG8_WAIT_L(0); PG8_BAR; PG8_MMA(0, 0, At, B0); PG8_MMA(0, 1, At, B1); PG8_BAR; PG8_SCHED;
	s_setprio 1
	s_waitcnt lgkmcnt(0)
	v_mfma_f32_16x16x32_bf16 v[58:61], v[130:133], v[182:185], 0
	v_mfma_f32_16x16x32_bf16 v[62:65], v[148:151], v[182:185], 0
	v_mfma_f32_16x16x32_bf16 v[42:45], v[130:133], v[190:193], 0
	v_mfma_f32_16x16x32_bf16 v[46:49], v[148:151], v[190:193], 0
	v_mfma_f32_16x16x32_bf16 v[26:29], v[130:133], v[200:203], 0
	v_mfma_f32_16x16x32_bf16 v[30:33], v[148:151], v[200:203], 0
	v_mfma_f32_16x16x32_bf16 v[10:13], v[130:133], v[208:211], 0
	v_mfma_f32_16x16x32_bf16 v[14:17], v[148:151], v[208:211], 0
	v_mfma_f32_16x16x32_bf16 v[58:61], v[144:147], v[186:189], v[58:61]
	v_mfma_f32_16x16x32_bf16 v[62:65], v[152:155], v[186:189], v[62:65]
	v_mfma_f32_16x16x32_bf16 v[42:45], v[144:147], v[196:199], v[42:45]
	v_mfma_f32_16x16x32_bf16 v[46:49], v[152:155], v[196:199], v[46:49]
	v_mfma_f32_16x16x32_bf16 v[26:29], v[144:147], v[204:207], v[26:29]
	v_mfma_f32_16x16x32_bf16 v[30:33], v[152:155], v[204:207], v[30:33]
	v_mfma_f32_16x16x32_bf16 v[10:13], v[144:147], v[212:215], v[10:13]
	v_mfma_f32_16x16x32_bf16 v[14:17], v[152:155], v[212:215], v[14:17]
	s_setprio 0
	s_setprio 1
	v_mfma_f32_16x16x32_bf16 v[50:53], v[156:159], v[182:185], 0
	v_mfma_f32_16x16x32_bf16 v[54:57], v[168:171], v[182:185], 0
	v_mfma_f32_16x16x32_bf16 v[34:37], v[156:159], v[190:193], 0
	v_mfma_f32_16x16x32_bf16 v[38:41], v[168:171], v[190:193], 0
	v_mfma_f32_16x16x32_bf16 v[18:21], v[156:159], v[200:203], 0
	v_mfma_f32_16x16x32_bf16 v[22:25], v[168:171], v[200:203], 0
	v_mfma_f32_16x16x32_bf16 v[6:9], v[156:159], v[208:211], 0
	v_mfma_f32_16x16x32_bf16 v[2:5], v[168:171], v[208:211], 0
	v_mfma_f32_16x16x32_bf16 v[50:53], v[160:163], v[186:189], v[50:53]
	v_mfma_f32_16x16x32_bf16 v[54:57], v[178:181], v[186:189], v[54:57]
	v_mfma_f32_16x16x32_bf16 v[34:37], v[160:163], v[196:199], v[34:37]
	v_mfma_f32_16x16x32_bf16 v[38:41], v[178:181], v[196:199], v[38:41]
	v_mfma_f32_16x16x32_bf16 v[18:21], v[160:163], v[204:207], v[18:21]
	v_mfma_f32_16x16x32_bf16 v[22:25], v[178:181], v[204:207], v[22:25]
	v_mfma_f32_16x16x32_bf16 v[6:9], v[160:163], v[212:215], v[6:9]
	v_mfma_f32_16x16x32_bf16 v[2:5], v[178:181], v[212:215], v[2:5]
	s_setprio 0
	s_barrier
	s_add_i32 s37, 0, 0x18000
	v_add_u32_e32 v0, s37, v174
	s_add_i32 s42, 0, 0x1c000
	ds_read_b128 v[130:133], v0
	ds_read_b128 v[144:147], v0 offset:1024
	ds_read_b128 v[148:151], v0 offset:2048
	ds_read_b128 v[152:155], v0 offset:3072
	v_add_u32_e32 v0, s42, v174
	ds_read_b128 v[156:159], v0
	ds_read_b128 v[160:163], v0 offset:1024
	ds_read_b128 v[168:171], v0 offset:2048
	ds_read_b128 v[178:181], v0 offset:3072
	s_add_u32 s20, s20, s18
	s_addc_u32 s21, s21, 0
	s_mov_b32 m0, s72
	v_lshl_add_u64 v[226:227], s[20:21], 0, v[134:135]
	ds_read_b128 v[182:185], v177 offset:32768
	ds_read_b128 v[186:189], v177 offset:33792
	ds_read_b128 v[190:193], v177 offset:34816
	ds_read_b128 v[196:199], v177 offset:35840
	ds_read_b128 v[200:203], v177 offset:36864
	ds_read_b128 v[204:207], v177 offset:37888
	ds_read_b128 v[208:211], v177 offset:38912
	ds_read_b128 v[212:215], v177 offset:39936
	global_load_lds_dwordx4 v[226:227], off
	v_lshl_add_u64 v[226:227], s[20:21], 0, v[136:137]
	s_mov_b32 m0, s73
	s_nop 0
	global_load_lds_dwordx4 v[226:227], off
	s_waitcnt vmcnt(8)
	s_waitcnt lgkmcnt(0)
	s_barrier
	s_setprio 1
	s_waitcnt lgkmcnt(0)
	v_mfma_f32_16x16x32_bf16 v[122:125], v[130:133], v[182:185], v[122:125]
	v_mfma_f32_16x16x32_bf16 v[126:129], v[148:151], v[182:185], v[126:129]
	v_mfma_f32_16x16x32_bf16 v[106:109], v[130:133], v[190:193], v[106:109]
	v_mfma_f32_16x16x32_bf16 v[110:113], v[148:151], v[190:193], v[110:113]
	v_mfma_f32_16x16x32_bf16 v[90:93], v[130:133], v[200:203], v[90:93]
	v_mfma_f32_16x16x32_bf16 v[94:97], v[148:151], v[200:203], v[94:97]
	v_mfma_f32_16x16x32_bf16 v[74:77], v[130:133], v[208:211], v[74:77]
	v_mfma_f32_16x16x32_bf16 v[78:81], v[148:151], v[208:211], v[78:81]
	v_mfma_f32_16x16x32_bf16 v[122:125], v[144:147], v[186:189], v[122:125]
	v_mfma_f32_16x16x32_bf16 v[126:129], v[152:155], v[186:189], v[126:129]
	v_mfma_f32_16x16x32_bf16 v[106:109], v[144:147], v[196:199], v[106:109]
	v_mfma_f32_16x16x32_bf16 v[110:113], v[152:155], v[196:199], v[110:113]
	v_mfma_f32_16x16x32_bf16 v[90:93], v[144:147], v[204:207], v[90:93]
	v_mfma_f32_16x16x32_bf16 v[94:97], v[152:155], v[204:207], v[94:97]
	v_mfma_f32_16x16x32_bf16 v[74:77], v[144:147], v[212:215], v[74:77]
	v_mfma_f32_16x16x32_bf16 v[78:81], v[152:155], v[212:215], v[78:81]
	s_setprio 0
	s_setprio 1
	v_mfma_f32_16x16x32_bf16 v[114:117], v[156:159], v[182:185], v[114:117]
	v_mfma_f32_16x16x32_bf16 v[118:121], v[168:171], v[182:185], v[118:121]
	v_mfma_f32_16x16x32_bf16 v[98:101], v[156:159], v[190:193], v[98:101]
	v_mfma_f32_16x16x32_bf16 v[102:105], v[168:171], v[190:193], v[102:105]
	v_mfma_f32_16x16x32_bf16 v[82:85], v[156:159], v[200:203], v[82:85]
	v_mfma_f32_16x16x32_bf16 v[86:89], v[168:171], v[200:203], v[86:89]
	v_mfma_f32_16x16x32_bf16 v[66:69], v[156:159], v[208:211], v[66:69]
	v_mfma_f32_16x16x32_bf16 v[70:73], v[168:171], v[208:211], v[70:73]
	v_mfma_f32_16x16x32_bf16 v[114:117], v[160:163], v[186:189], v[114:117]
	v_mfma_f32_16x16x32_bf16 v[118:121], v[178:181], v[186:189], v[118:121]
	v_mfma_f32_16x16x32_bf16 v[98:101], v[160:163], v[196:199], v[98:101]
	v_mfma_f32_16x16x32_bf16 v[102:105], v[178:181], v[196:199], v[102:105]
	v_mfma_f32_16x16x32_bf16 v[82:85], v[160:163], v[204:207], v[82:85]
	v_mfma_f32_16x16x32_bf16 v[86:89], v[178:181], v[204:207], v[86:89]
	v_mfma_f32_16x16x32_bf16 v[66:69], v[160:163], v[212:215], v[66:69]
	v_mfma_f32_16x16x32_bf16 v[70:73], v[178:181], v[212:215], v[70:73]
	s_setprio 0
	s_barrier
; #define PG8_STAGE(bufoff, gbase, voff) do { _Pragma("unroll") for (int _i = 0; _i < 2; ++_i) \
;         __builtin_amdgcn_global_load_lds((const unsigned*)((const char*)(gbase) + (voff)[_i]), (LAS unsigned*)(lds + (bufoff) + ldsw + _i * 8192), 16, 0, 0); } while (0)
; #define PG8_LDA(dst, b, h) do { _Pragma("unroll") for (int m = 0; m < 4; ++m) _Pragma("unroll") for (int k = 0; k < 2; ++k) dst[m][k] = *(const LAS bf16x8*)(lds + PG8_SA(b, h) + aoff + m * 2048 + k * 1024); } while (0)
; #define PG8_MMA(ai, bj, At, Bt) do { __builtin_amdgcn_s_setprio(1); _Pragma("unroll") for (int m = 0; m < 4; ++m) _Pragma("unroll") for (int n = 0; n < 2; ++n) _Pragma("unroll") for (int k = 0; k < 2; ++k) \
;         acc[ai][bj][m][n] = __builtin_amdgcn_mfma_f32_16x16x32_bf16(Bt[n][k], At[m][k], acc[ai][bj][m][n], 0, 0, 0); __builtin_amdgcn_s_setprio(0); } while (0)
; #define PG8_WAIT_V(n) asm volatile("s_waitcnt vmcnt(" #n ")" ::: "memory")
; #define PG8_WAIT_L(n) asm volatile("s_waitcnt lgkmcnt(" #n ")" ::: "memory")
; #define PG8_BAR __builtin_amdgcn_s_barrier()
; #define PG8_SCHED __builtin_amdgcn_sched_barrier(0)
; template <bool PERM>
; __device__ __forceinline__ void gemm_phase(LAS unsigned char* lds, const Gemm g, const Sched& S, const EpiDesc& E, const Ctx& C) {
;     ...
;             PG8_LDA(At, 1, 1); PG8_STAGE(PG8_SB(1, 0), b3, voffB); PG8_STAGE(PG8_SB(1, 1), b3 + hstepB, voffB); PG8_STAGE(PG8_SA(1, 0), a3, voffA);
;             PG8_WAIT_V(8); PG8_WAIT_L(0); PG8_BAR; PG8_MMA(1, 0, At, B0); PG8_MMA(1, 1, At, B1); PG8_BAR; PG8_SCHED;
;         }
	s_add_i32 s20, s37, s69
	v_lshl_add_u64 v[164:165], v[164:165], 0, s[48:49]
	s_mov_b32 m0, s20
	ds_read_b128 v[182:185], v177 offset:49152
	ds_read_b128 v[186:189], v177 offset:50176
	ds_read_b128 v[190:193], v177 offset:51200
	ds_read_b128 v[196:199], v177 offset:52224
	ds_read_b128 v[200:203], v177 offset:53248
	ds_read_b128 v[204:207], v177 offset:54272
	ds_read_b128 v[208:211], v177 offset:55296
	ds_read_b128 v[212:215], v177 offset:56320
	global_load_lds_dwordx4 v[164:165], off
	v_lshl_add_u64 v[164:165], v[216:217], 0, s[48:49]
	s_add_i32 m0, s20, 0x2000
	s_add_i32 s20, s42, s69
	global_load_lds_dwordx4 v[164:165], off
	v_lshl_add_u64 v[164:165], v[218:219], 0, s[48:49]
	s_mov_b32 m0, s20
	s_nop 0
	global_load_lds_dwordx4 v[164:165], off
	v_lshl_add_u64 v[164:165], v[220:221], 0, s[48:49]
	s_add_i32 m0, s20, 0x2000
	s_nop 0
	global_load_lds_dwordx4 v[164:165], off
	v_lshl_add_u64 v[164:165], v[222:223], 0, s[48:49]
	s_mov_b32 m0, s75
	s_nop 0
	global_load_lds_dwordx4 v[164:165], off
	v_lshl_add_u64 v[164:165], v[224:225], 0, s[48:49]
	s_mov_b32 m0, s76
	s_nop 0
	global_load_lds_dwordx4 v[164:165], off
	s_waitcnt vmcnt(8)
	s_waitcnt lgkmcnt(0)
	s_barrier
	s_setprio 1
	s_waitcnt lgkmcnt(0)
	v_mfma_f32_16x16x32_bf16 v[58:61], v[130:133], v[182:185], v[58:61]
	v_mfma_f32_16x16x32_bf16 v[62:65], v[148:151], v[182:185], v[62:65]
	v_mfma_f32_16x16x32_bf16 v[42:45], v[130:133], v[190:193], v[42:45]
	v_mfma_f32_16x16x32_bf16 v[46:49], v[148:151], v[190:193], v[46:49]
	v_mfma_f32_16x16x32_bf16 v[26:29], v[130:133], v[200:203], v[26:29]
	v_mfma_f32_16x16x32_bf16 v[30:33], v[148:151], v[200:203], v[30:33]
	v_mfma_f32_16x16x32_bf16 v[10:13], v[130:133], v[208:211], v[10:13]
	v_mfma_f32_16x16x32_bf16 v[14:17], v[148:151], v[208:211], v[14:17]
	v_mfma_f32_16x16x32_bf16 v[58:61], v[144:147], v[186:189], v[58:61]
	v_mfma_f32_16x16x32_bf16 v[62:65], v[152:155], v[186:189], v[62:65]
	v_mfma_f32_16x16x32_bf16 v[42:45], v[144:147], v[196:199], v[42:45]
	v_mfma_f32_16x16x32_bf16 v[46:49], v[152:155], v[196:199], v[46:49]
	v_mfma_f32_16x16x32_bf16 v[26:29], v[144:147], v[204:207], v[26:29]
	v_mfma_f32_16x16x32_bf16 v[30:33], v[152:155], v[204:207], v[30:33]
	v_mfma_f32_16x16x32_bf16 v[10:13], v[144:147], v[212:215], v[10:13]
	v_mfma_f32_16x16x32_bf16 v[14:17], v[152:155], v[212:215], v[14:17]
	s_setprio 0
	s_setprio 1
	v_mfma_f32_16x16x32_bf16 v[50:53], v[156:159], v[182:185], v[50:53]
	v_mfma_f32_16x16x32_bf16 v[54:57], v[168:171], v[182:185], v[54:57]
	v_mfma_f32_16x16x32_bf16 v[34:37], v[156:159], v[190:193], v[34:37]
	v_mfma_f32_16x16x32_bf16 v[38:41], v[168:171], v[190:193], v[38:41]
	v_mfma_f32_16x16x32_bf16 v[18:21], v[156:159], v[200:203], v[18:21]
	v_mfma_f32_16x16x32_bf16 v[22:25], v[168:171], v[200:203], v[22:25]
	v_mfma_f32_16x16x32_bf16 v[6:9], v[156:159], v[208:211], v[6:9]
	v_mfma_f32_16x16x32_bf16 v[2:5], v[168:171], v[208:211], v[2:5]
	v_mfma_f32_16x16x32_bf16 v[50:53], v[160:163], v[186:189], v[50:53]
	v_mfma_f32_16x16x32_bf16 v[54:57], v[178:181], v[186:189], v[54:57]
	v_mfma_f32_16x16x32_bf16 v[34:37], v[160:163], v[196:199], v[34:37]
	v_mfma_f32_16x16x32_bf16 v[38:41], v[178:181], v[196:199], v[38:41]
	v_mfma_f32_16x16x32_bf16 v[18:21], v[160:163], v[204:207], v[18:21]
	v_mfma_f32_16x16x32_bf16 v[22:25], v[178:181], v[204:207], v[22:25]
	v_mfma_f32_16x16x32_bf16 v[6:9], v[160:163], v[212:215], v[6:9]
	v_mfma_f32_16x16x32_bf16 v[2:5], v[178:181], v[212:215], v[2:5]
	s_setprio 0
	s_barrier
	s_add_u32 s2, s2, 0x100
	s_addc_u32 s3, s3, 0
	s_add_u32 s23, s23, 0x100
	s_addc_u32 s29, s29, 0
	s_cmp_ge_i32 s36, s28
	s_mov_b32 s20, s36
	s_cbranch_scc1 .Lkb_exit

; #define PG8_BAR __builtin_amdgcn_s_barrier()
; template <bool PERM>
; __device__ __forceinline__ void gemm_phase(LAS unsigned char* lds, const Gemm g, const Sched& S, const EpiDesc& E, const Ctx& C) {
;     ...
;         if (wr == 0) PG8_BAR;
;         if (PERM) {
;             if ((PERM_MASK & 1) && E.kind == EK_SWIGLU) epilogue_p<EK_SWIGLU>(acc, cur, E, C, wr, wc, fr, fq);
;             else if ((PERM_MASK & 2) && E.kind == EK_RESID) epilogue_p<EK_RESID>(acc, cur, E, C, wr, wc, fr, fq);
;             else if ((PERM_MASK & 4) && E.kind == EK_PROJ) epilogue_p<EK_PROJ>(acc, cur, E, C, wr, wc, fr, fq);
;             else if ((PERM_MASK & 8) && E.kind == EK_BRANCH) epilogue_p<EK_BRANCH>(acc, cur, E, C, wr, wc, fr, fq);
;         } else {
;             if (!(PERM_MASK & 1) && E.kind == EK_SWIGLU) epilogue<EK_SWIGLU>(acc, cur, E, C, wr, wc, fr, fq);
.Lkb_exit:
	s_and_b64 vcc, exec, s[56:57]
	s_cbranch_vccnz .LBB0_249
